# P7 row loop: next row's 16 loads prefetched at loop top into spare registers (doubles bytes in flight per wave)
# baseline (speedup 1.0000x reference)
; __device__ __forceinline__ void p7_rows(const Params& P, LAS unsigned char* lds, int G) {
;     ...
;     for (int m = blockIdx.x * 8 + wave; m < M; m += G * 8) {
;         const int b = m >> 13; const f32x4* xr = (const f32x4*)(P.x + (size_t)m * DM) + lane; const u32x2* orow = (const u32x2*)(O + (size_t)m * DM) + lane;
;         f32x4 v[8], xv[8]; float ss = 0.f;
; #pragma unroll
;         for (int j = 0; j < 8; ++j) xv[j] = __builtin_nontemporal_load(xr + 64 * j);
; #pragma unroll
;         for (int j = 0; j < 8; ++j) { const u32x2 w = __builtin_nontemporal_load(orow + 64 * j); v[j][0] = __uint_as_float(w.x << 16); v[j][1] = __uint_as_float(w.x & 0xffff0000u); v[j][2] = __uint_as_float(w.y << 16); v[j][3] = __uint_as_float(w.y & 0xffff0000u);
.LBB0_801:
	s_or_b64 exec, exec, s[22:23]
	v_ashrrev_i32_e32 v1, 6, v0
	s_and_b32 s1, s2, 7
	s_lshl_b32 s1, s1, 11
	s_lshr_b32 s0, s2, 3
	s_lshl_b32 s0, s0, 3
	s_add_i32 s0, s0, s1
	s_lshl_b32 s1, s2, 3
	s_cmpk_eq_u32 s92, 0x100
	s_cselect_b32 s0, s0, s1
	s_waitcnt lgkmcnt(0)
	s_barrier
	v_add_u32_e32 v32, s0, v1
	s_movk_i32 s0, 0x4000
	v_cmp_gt_i32_e32 vcc, s0, v32
	s_and_saveexec_b64 s[0:1], vcc
	s_cbranch_execz .LBB0_804
	v_and_b32_e32 v2, 63, v0
	v_mbcnt_hi_u32_b32 v0, -1, v208
	v_and_b32_e32 v1, 64, v0
	v_add_u32_e32 v1, 64, v1
	v_xor_b32_e32 v3, 1, v0
	v_cmp_lt_i32_e32 vcc, v3, v1
	v_ashrrev_i32_e32 v33, 31, v32
	s_mov_b64 s[22:23], 0x1000
	v_cndmask_b32_e32 v3, v0, v3, vcc
	v_lshlrev_b32_e32 v74, 2, v3
	v_xor_b32_e32 v3, 2, v0
	v_cmp_lt_i32_e32 vcc, v3, v1
	s_cmpk_eq_u32 s92, 0x100
	s_cselect_b32 s42, 0x100, s42
	s_ashr_i32 s43, s42, 31
	s_mov_b64 s[26:27], 0x1a000000
	v_cndmask_b32_e32 v3, v0, v3, vcc
	v_lshlrev_b32_e32 v75, 2, v3
	v_xor_b32_e32 v3, 4, v0
	v_cmp_lt_i32_e32 vcc, v3, v1
	s_mov_b64 s[30:31], 0
	s_mov_b32 s3, 0x800000
	v_cndmask_b32_e32 v3, v0, v3, vcc
	v_lshlrev_b32_e32 v76, 2, v3
	v_xor_b32_e32 v3, 8, v0
	v_cmp_lt_i32_e32 vcc, v3, v1
	s_nop 1
	v_cndmask_b32_e32 v3, v0, v3, vcc
	v_lshlrev_b32_e32 v77, 2, v3
	v_xor_b32_e32 v3, 16, v0
	v_cmp_lt_i32_e32 vcc, v3, v1
	s_nop 1
	v_cndmask_b32_e32 v3, v0, v3, vcc
	v_lshlrev_b32_e32 v78, 2, v3
	v_xor_b32_e32 v3, 32, v0
	v_cmp_lt_i32_e32 vcc, v3, v1
	s_nop 1
	v_cndmask_b32_e32 v0, v0, v3, vcc
	v_lshlrev_b32_e32 v79, 2, v0
	v_lshlrev_b32_e32 v3, 4, v2
	v_lshlrev_b64 v[0:1], 13, v[32:33]
	v_or_b32_e32 v0, v0, v3
	v_lshl_add_u64 v[0:1], s[60:61], 0, v[0:1]
	v_lshl_add_u64 v[34:35], v[0:1], 0, s[22:23]
	v_lshlrev_b64 v[0:1], 12, v[32:33]
	v_lshl_or_b32 v0, v2, 3, v0
	v_lshl_add_u64 v[0:1], s[58:59], 0, v[0:1]
	v_add_u32_e32 v80, 0, v3
	s_lshl_b64 s[22:23], s[42:43], 13
	v_lshl_add_u64 v[36:37], v[0:1], 0, s[26:27]
	s_lshl_b64 s[26:27], s[42:43], 12
	v_mov_b32_e32 v33, 0x358637bd
	v_add_co_u32_e32 v204, vcc, 0xf0800000, v36
	s_mov_b32 s33, 0xf0801000
	s_nop 0
	v_addc_co_u32_e32 v205, vcc, -1, v37, vcc
	v_add_co_u32_e32 v206, vcc, s33, v36
	global_load_dwordx4 v[128:131], v[34:35], off offset:-4096 nt
	global_load_dwordx4 v[132:135], v[34:35], off offset:-3072 nt
	global_load_dwordx4 v[136:139], v[34:35], off offset:-2048 nt
	global_load_dwordx4 v[140:143], v[34:35], off offset:-1024 nt
	global_load_dwordx4 v[144:147], v[34:35], off nt
	global_load_dwordx4 v[148:151], v[34:35], off offset:1024 nt
	global_load_dwordx4 v[152:155], v[34:35], off offset:2048 nt
	global_load_dwordx4 v[156:159], v[34:35], off offset:3072 nt
	v_addc_co_u32_e32 v207, vcc, -1, v37, vcc
	global_load_dwordx2 v[160:161], v[204:205], off nt
	global_load_dwordx2 v[162:163], v[206:207], off offset:-3584 nt
	global_load_dwordx2 v[164:165], v[206:207], off offset:-3072 nt
	global_load_dwordx2 v[166:167], v[206:207], off offset:-2560 nt
	global_load_dwordx2 v[170:171], v[206:207], off offset:-2048 nt
	global_load_dwordx2 v[172:173], v[206:207], off offset:-1536 nt
	global_load_dwordx2 v[174:175], v[206:207], off offset:-1024 nt
	global_load_dwordx2 v[202:203], v[206:207], off offset:-512 nt
	v_lshl_add_u64 v[34:35], v[34:35], 0, s[22:23]
	v_lshl_add_u64 v[210:211], v[36:37], 0, s[26:27]
	s_waitcnt vmcnt(0)
.LBB0_803:
	s_waitcnt vmcnt(16)
	v_mov_b32_e32 v28, v128
	v_mov_b32_e32 v29, v129
	v_mov_b32_e32 v30, v130
	v_mov_b32_e32 v31, v131
	v_mov_b32_e32 v24, v132
	v_mov_b32_e32 v25, v133
	v_mov_b32_e32 v26, v134
	v_mov_b32_e32 v27, v135
	v_mov_b32_e32 v20, v136
	v_mov_b32_e32 v21, v137
	v_mov_b32_e32 v22, v138
	v_mov_b32_e32 v23, v139
	v_mov_b32_e32 v16, v140
	v_mov_b32_e32 v17, v141
	v_mov_b32_e32 v18, v142
	v_mov_b32_e32 v19, v143
	v_mov_b32_e32 v12, v144
	v_mov_b32_e32 v13, v145
	v_mov_b32_e32 v14, v146
	v_mov_b32_e32 v15, v147
	v_mov_b32_e32 v8, v148
	v_mov_b32_e32 v9, v149
	v_mov_b32_e32 v10, v150
	v_mov_b32_e32 v11, v151
	v_mov_b32_e32 v4, v152
	v_mov_b32_e32 v5, v153
	v_mov_b32_e32 v6, v154
	v_mov_b32_e32 v7, v155
	v_mov_b32_e32 v0, v156
	v_mov_b32_e32 v1, v157
	v_mov_b32_e32 v2, v158
	v_mov_b32_e32 v3, v159
	v_mov_b32_e32 v38, v160
	v_mov_b32_e32 v39, v161
	v_mov_b32_e32 v42, v162
	v_mov_b32_e32 v43, v163
	v_mov_b32_e32 v44, v164
	v_mov_b32_e32 v45, v165
	v_mov_b32_e32 v90, v166
	v_mov_b32_e32 v91, v167
	v_mov_b32_e32 v92, v170
	v_mov_b32_e32 v93, v171
	v_mov_b32_e32 v94, v172
	v_mov_b32_e32 v95, v173
	v_mov_b32_e32 v96, v174
	v_mov_b32_e32 v97, v175
	v_mov_b32_e32 v98, v202
	v_mov_b32_e32 v99, v203
	s_and_b32 s6, s2, 7
	s_lshl_b32 s6, s6, 11
	s_addk_i32 s6, 0x7ff
	s_cmpk_eq_u32 s92, 0x100
	s_cselect_b32 s6, s6, 0x3fff
	v_add_u32_e32 v209, s42, v32
	v_cmp_ge_i32_e32 vcc, s6, v209
	s_and_saveexec_b64 s[6:7], vcc
	v_add_co_u32_e32 v204, vcc, 0xf0800000, v210
	s_mov_b32 s33, 0xf0801000
	s_nop 0
	v_addc_co_u32_e32 v205, vcc, -1, v211, vcc
	v_add_co_u32_e32 v206, vcc, s33, v210
	global_load_dwordx4 v[128:131], v[34:35], off offset:-4096 nt
	global_load_dwordx4 v[132:135], v[34:35], off offset:-3072 nt
	global_load_dwordx4 v[136:139], v[34:35], off offset:-2048 nt
	global_load_dwordx4 v[140:143], v[34:35], off offset:-1024 nt
	global_load_dwordx4 v[144:147], v[34:35], off nt
	global_load_dwordx4 v[148:151], v[34:35], off offset:1024 nt
	global_load_dwordx4 v[152:155], v[34:35], off offset:2048 nt
	global_load_dwordx4 v[156:159], v[34:35], off offset:3072 nt
	v_addc_co_u32_e32 v207, vcc, -1, v211, vcc
	global_load_dwordx2 v[160:161], v[204:205], off nt
	global_load_dwordx2 v[162:163], v[206:207], off offset:-3584 nt
	global_load_dwordx2 v[164:165], v[206:207], off offset:-3072 nt
	global_load_dwordx2 v[166:167], v[206:207], off offset:-2560 nt
; #define LAS __attribute__((address_space(3)))
; __device__ __forceinline__ unsigned pk2(float lo, float hi) { return pg8::cvtpk(lo, hi); }
; __device__ __forceinline__ void p7_rows(const Params& P, LAS unsigned char* lds, int G) {
;     ...
;         for (int j = 0; j < 8; ++j) { const u32x2 w = __builtin_nontemporal_load(orow + 64 * j); v[j][0] = __uint_as_float(w.x << 16); v[j][1] = __uint_as_float(w.x & 0xffff0000u); v[j][2] = __uint_as_float(w.y << 16); v[j][3] = __uint_as_float(w.y & 0xffff0000u);
;             ss += (v[j][0] * v[j][0] + v[j][1] * v[j][1]) + (v[j][2] * v[j][2] + v[j][3] * v[j][3]); }
;         const float rstd = rsqrtf(wave_sum(ss) * (1.0f / DM) + RMS_EPS);
;         float s2 = 0.f; u32x2* x1r = (u32x2*)((bf16_t*)(P.ws + WS_X1) + (size_t)m * DM) + lane;
; #pragma unroll
;         for (int j = 0; j < 8; ++j) { const f32x4 a = *(const LAS f32x4*)(TA + b * DM + 256 * j + 4 * lane); const f32x4 x1 = xv[j] + v[j] * rstd * a; v[j] = x1; { u32x2 w; w.x = pk2(x1[0], x1[1]); w.y = pk2(x1[2], x1[3]); __builtin_nontemporal_store(w, x1r + 64 * j); }
	global_load_dwordx2 v[170:171], v[206:207], off offset:-2048 nt
	global_load_dwordx2 v[172:173], v[206:207], off offset:-1536 nt
	global_load_dwordx2 v[174:175], v[206:207], off offset:-1024 nt
	global_load_dwordx2 v[202:203], v[206:207], off offset:-512 nt
	s_or_b64 exec, exec, s[6:7]
	v_lshl_add_u64 v[34:35], v[34:35], 0, s[22:23]
	v_lshl_add_u64 v[210:211], v[210:211], 0, s[26:27]
	s_mov_b32 s33, 0xec800000
	v_and_b32_e32 v67, 0xffff0000, v38
	v_and_b32_e32 v69, 0xffff0000, v39
	v_lshlrev_b32_e32 v66, 16, v38
	v_lshlrev_b32_e32 v58, 16, v44
	v_and_b32_e32 v59, 0xffff0000, v44
	v_lshlrev_b32_e32 v60, 16, v45
	v_and_b32_e32 v61, 0xffff0000, v45
	v_lshlrev_b32_e32 v68, 16, v39
	v_mul_f32_e32 v38, v69, v69
	v_and_b32_e32 v73, 0xffff0000, v43
	v_and_b32_e32 v72, 0xffff0000, v42
	v_pk_fma_f32 v[38:39], v[68:69], v[68:69], v[38:39] op_sel_hi:[1,1,0]
	v_lshlrev_b32_e32 v71, 16, v43
	v_lshlrev_b32_e32 v70, 16, v42
	v_pk_mul_f32 v[42:43], v[72:73], v[72:73]
	v_mov_b32_e32 v46, v38
	v_pk_fma_f32 v[42:43], v[70:71], v[70:71], v[42:43]
	v_mov_b32_e32 v44, v90
	v_mov_b32_e32 v45, v91
	v_lshlrev_b32_e32 v55, 16, v44
	v_and_b32_e32 v51, 0xffff0000, v44
	v_mul_f32_e32 v44, v67, v67
	v_lshlrev_b32_e32 v48, 16, v45
	v_and_b32_e32 v49, 0xffff0000, v45
	v_pk_fma_f32 v[44:45], v[66:67], v[66:67], v[44:45] op_sel_hi:[1,1,0]
	v_mov_b32_e32 v47, v55
	v_mov_b32_e32 v54, v44
	v_mul_f32_e32 v50, v51, v51
	v_pk_add_f32 v[38:39], v[44:45], v[38:39]
	v_pk_mul_f32 v[44:45], v[54:55], v[46:47]
	v_pk_add_f32 v[42:43], v[42:43], v[42:43] op_sel:[0,1] op_sel_hi:[1,0]
	v_mov_b32_e32 v39, v45
	v_mov_b32_e32 v43, v50
	v_pk_add_f32 v[38:39], v[38:39], v[42:43]
	v_mul_f32_e32 v42, v59, v59
	v_mul_f32_e32 v44, v61, v61
	v_mul_f32_e32 v52, v48, v48
	v_mul_f32_e32 v53, v49, v49
	v_pk_fma_f32 v[42:43], v[58:59], v[58:59], v[42:43] op_sel_hi:[1,1,0]
	v_pk_fma_f32 v[44:45], v[60:61], v[60:61], v[44:45] op_sel_hi:[1,1,0]
	v_mov_b32_e32 v43, v52
	v_mov_b32_e32 v45, v53
	v_pk_add_f32 v[42:43], v[42:43], v[44:45]
	s_nop 0
	v_pk_add_f32 v[82:83], v[38:39], v[42:43]
	v_pk_add_f32 v[82:83], v[82:83], v[82:83] op_sel:[0,1] op_sel_hi:[1,0]
	v_mov_b32_e32 v38, v92
	v_mov_b32_e32 v39, v93
	v_and_b32_e32 v65, 0xffff0000, v39
	v_and_b32_e32 v64, 0xffff0000, v38
	v_lshlrev_b32_e32 v63, 16, v39
	v_lshlrev_b32_e32 v62, 16, v38
	v_pk_mul_f32 v[38:39], v[64:65], v[64:65]
	v_mov_b32_e32 v42, v82
	v_pk_fma_f32 v[38:39], v[62:63], v[62:63], v[38:39]
	s_nop 0
	v_pk_add_f32 v[84:85], v[38:39], v[38:39] op_sel:[0,1] op_sel_hi:[1,0]
	v_mov_b32_e32 v88, v84
	v_pk_add_f32 v[82:83], v[82:83], v[84:85]
	v_mov_b32_e32 v38, v94
	v_mov_b32_e32 v39, v95
	v_and_b32_e32 v57, 0xffff0000, v39
	v_and_b32_e32 v56, 0xffff0000, v38
	v_lshlrev_b32_e32 v53, 16, v39
	v_lshlrev_b32_e32 v52, 16, v38
	v_pk_mul_f32 v[38:39], v[56:57], v[56:57]
	s_nop 0
	v_pk_fma_f32 v[86:87], v[52:53], v[52:53], v[38:39]
	v_mov_b32_e32 v38, v96
	v_mov_b32_e32 v39, v97
	v_lshlrev_b32_e32 v44, 16, v38
	v_and_b32_e32 v45, 0xffff0000, v38
	v_lshlrev_b32_e32 v46, 16, v39
	v_and_b32_e32 v47, 0xffff0000, v39
	v_mov_b32_e32 v38, v98
	v_mov_b32_e32 v39, v99
	v_lshlrev_b32_e32 v43, 16, v38
	v_mov_b32_e32 v89, v43
	v_and_b32_e32 v41, 0xffff0000, v38
	v_pk_mul_f32 v[84:85], v[42:43], v[88:89]
	v_mul_f32_e32 v40, v41, v41
	v_mov_b32_e32 v83, v85
	v_pk_add_f32 v[84:85], v[86:87], v[86:87] op_sel:[0,1] op_sel_hi:[1,0]
	v_lshlrev_b32_e32 v38, 16, v39
	v_mov_b32_e32 v85, v40
	v_mul_f32_e32 v40, v45, v45
	v_and_b32_e32 v39, 0xffff0000, v39
	v_pk_add_f32 v[82:83], v[82:83], v[84:85]
	v_pk_fma_f32 v[84:85], v[44:45], v[44:45], v[40:41] op_sel_hi:[1,1,0]
	v_mul_f32_e32 v40, v47, v47
	v_mul_f32_e32 v50, v38, v38
	v_mul_f32_e32 v54, v39, v39
	v_pk_fma_f32 v[86:87], v[46:47], v[46:47], v[40:41] op_sel_hi:[1,1,0]
	v_mov_b32_e32 v85, v50
	v_mov_b32_e32 v87, v54
	v_pk_add_f32 v[84:85], v[84:85], v[86:87]
	v_mov_b32_e32 v50, v55
	v_pk_add_f32 v[82:83], v[82:83], v[84:85]
	s_nop 0
	v_add_f32_e32 v40, v82, v83
	s_nop 1
	v_add_f32_dpp v40, v40, v40 quad_perm:[1,0,3,2] row_mask:0xf bank_mask:0xf
	s_nop 1
	v_add_f32_dpp v40, v40, v40 quad_perm:[2,3,0,1] row_mask:0xf bank_mask:0xf
	s_nop 1
	v_add_f32_dpp v40, v40, v40 row_half_mirror row_mask:0xf bank_mask:0xf
	s_nop 1
	v_add_f32_dpp v40, v40, v40 row_mirror row_mask:0xf bank_mask:0xf
	v_mov_b32_e32 v42, v40
	s_nop 1
	v_permlane16_swap_b32_e32 v42, v40
	v_add_f32_e32 v40, v40, v42
	v_mov_b32_e32 v42, v40
	s_nop 1
	v_permlane32_swap_b32_e32 v42, v40
	v_add_f32_e32 v40, v40, v42
	s_waitcnt lgkmcnt(0)
	v_fmamk_f32 v40, v40, 0x3a000000, v33
	v_cmp_gt_f32_e32 vcc, s3, v40
	v_mul_f32_e32 v42, 0x4b800000, v40
	s_nop 0
	v_cndmask_b32_e32 v40, v40, v42, vcc
	v_rsq_f32_e32 v40, v40
	s_nop 0
	v_mul_f32_e32 v42, 0x45800000, v40
	v_cndmask_b32_e32 v42, v40, v42, vcc
	v_and_b32_e32 v40, 0xffffe000, v32
	v_add_u32_e32 v54, v80, v40
	ds_read_b128 v[82:85], v54
	v_pk_mul_f32 v[66:67], v[42:43], v[66:67] op_sel_hi:[0,1]
	v_pk_mul_f32 v[68:69], v[42:43], v[68:69] op_sel_hi:[0,1]
	v_pk_mul_f32 v[50:51], v[50:51], v[42:43] op_sel_hi:[1,0]
	v_pk_mul_f32 v[48:49], v[48:49], v[42:43] op_sel_hi:[1,0]
	s_waitcnt lgkmcnt(0)
	v_pk_fma_f32 v[84:85], v[84:85], v[68:69], v[30:31]
	v_pk_fma_f32 v[82:83], v[82:83], v[66:67], v[28:29]
	v_cvt_pk_bf16_f32 v29, v84, v85
	v_cvt_pk_bf16_f32 v28, v82, v83
	global_store_dwordx2 v[36:37], v[28:29], off nt
	ds_read_b128 v[28:31], v54 offset:1024
	v_mov_b32_e32 v66, v70
	v_mov_b32_e32 v67, v72
	v_mov_b32_e32 v72, v71
	v_pk_mul_f32 v[66:67], v[42:43], v[66:67] op_sel_hi:[0,1]
	v_pk_mul_f32 v[68:69], v[42:43], v[72:73] op_sel_hi:[0,1]
	s_waitcnt lgkmcnt(0)
; #define LAS __attribute__((address_space(3)))
; __device__ __forceinline__ unsigned pk2(float lo, float hi) { return pg8::cvtpk(lo, hi); }
; __device__ __forceinline__ void p7_rows(const Params& P, LAS unsigned char* lds, int G) {
;     ...
;         for (int j = 0; j < 8; ++j) { const f32x4 a = *(const LAS f32x4*)(TA + b * DM + 256 * j + 4 * lane); const f32x4 x1 = xv[j] + v[j] * rstd * a; v[j] = x1; { u32x2 w; w.x = pk2(x1[0], x1[1]); w.y = pk2(x1[2], x1[3]); __builtin_nontemporal_store(w, x1r + 64 * j); }
;             s2 += (x1[0] * x1[0] + x1[1] * x1[1]) + (x1[2] * x1[2] + x1[3] * x1[3]); }
;         const float rstd2 = rsqrtf(wave_sum(s2) * (1.0f / DM) + RMS_EPS);
	v_pk_fma_f32 v[26:27], v[30:31], v[68:69], v[26:27]
	v_pk_fma_f32 v[28:29], v[28:29], v[66:67], v[24:25]
	v_cvt_pk_bf16_f32 v25, v26, v27
	v_cvt_pk_bf16_f32 v24, v28, v29
	v_mov_b32_e32 v30, v83
	v_mov_b32_e32 v31, v29
	global_store_dwordx2 v[36:37], v[24:25], off offset:512 nt
	v_mov_b32_e32 v24, v82
	v_mov_b32_e32 v25, v28
	v_pk_mul_f32 v[30:31], v[30:31], v[30:31]
	v_mov_b32_e32 v66, v85
	v_mov_b32_e32 v67, v27
	v_pk_fma_f32 v[24:25], v[24:25], v[24:25], v[30:31]
	v_mov_b32_e32 v30, v84
	v_mov_b32_e32 v31, v26
	v_pk_mul_f32 v[66:67], v[66:67], v[66:67]
	v_pk_mul_f32 v[44:45], v[42:43], v[44:45] op_sel_hi:[0,1]
	v_pk_fma_f32 v[30:31], v[30:31], v[30:31], v[66:67]
	ds_read_b128 v[66:69], v54 offset:2048
	v_pk_add_f32 v[24:25], v[24:25], v[30:31]
	v_pk_mul_f32 v[30:31], v[42:43], v[58:59] op_sel_hi:[0,1]
	v_pk_mul_f32 v[58:59], v[42:43], v[60:61] op_sel_hi:[0,1]
	v_pk_add_f32 v[24:25], v[24:25], v[24:25] op_sel_hi:[0,1]
	s_waitcnt lgkmcnt(0)
	v_pk_fma_f32 v[22:23], v[68:69], v[58:59], v[22:23]
	v_pk_fma_f32 v[20:21], v[66:67], v[30:31], v[20:21]
	v_cvt_pk_bf16_f32 v31, v22, v23
	v_cvt_pk_bf16_f32 v30, v20, v21
	global_store_dwordx2 v[36:37], v[30:31], off offset:1024 nt
	v_pk_mul_f32 v[30:31], v[22:23], v[22:23]
	v_pk_mul_f32 v[58:59], v[20:21], v[20:21]
	v_mov_b32_e32 v66, v62
	v_pk_mov_b32 v[60:61], v[58:59], v[30:31] op_sel:[1,0]
	v_mov_b32_e32 v59, v31
	v_pk_add_f32 v[30:31], v[60:61], v[58:59]
	ds_read_b128 v[58:61], v54 offset:3072
	v_mov_b32_e32 v67, v64
	v_mov_b32_e32 v64, v63
	v_pk_mul_f32 v[66:67], v[42:43], v[66:67] op_sel_hi:[0,1]
	v_pk_mul_f32 v[62:63], v[42:43], v[64:65] op_sel_hi:[0,1]
	s_waitcnt lgkmcnt(0)
	v_pk_fma_f32 v[18:19], v[60:61], v[48:49], v[18:19]
	v_pk_fma_f32 v[16:17], v[58:59], v[50:51], v[16:17]
	v_cvt_pk_bf16_f32 v49, v18, v19
	v_cvt_pk_bf16_f32 v48, v16, v17
	global_store_dwordx2 v[36:37], v[48:49], off offset:1536 nt
	ds_read_b128 v[48:51], v54 offset:4096
	v_mul_f32_e32 v24, v16, v16
	v_pk_fma_f32 v[58:59], v[16:17], v[16:17], v[24:25] op_sel_hi:[1,1,0]
	v_mul_f32_e32 v24, v18, v18
	v_pk_add_f32 v[30:31], v[30:31], v[30:31] op_sel_hi:[0,1]
	v_pk_fma_f32 v[60:61], v[18:19], v[18:19], v[24:25] op_sel_hi:[1,1,0]
	s_waitcnt lgkmcnt(0)
	v_pk_fma_f32 v[14:15], v[50:51], v[62:63], v[14:15]
	v_pk_fma_f32 v[12:13], v[48:49], v[66:67], v[12:13]
	v_cvt_pk_bf16_f32 v49, v14, v15
	v_cvt_pk_bf16_f32 v48, v12, v13
	v_mul_f32_e32 v58, v12, v12
	v_mul_f32_e32 v60, v13, v13
	v_mul_f32_e32 v30, v14, v14
	v_mul_f32_e32 v24, v15, v15
	global_store_dwordx2 v[36:37], v[48:49], off offset:2048 nt
	v_pk_add_f32 v[48:49], v[58:59], v[60:61]
	v_pk_add_f32 v[24:25], v[30:31], v[24:25]
	v_mov_b32_e32 v30, v52
	v_pk_add_f32 v[24:25], v[48:49], v[24:25]
	ds_read_b128 v[48:51], v54 offset:5120
	v_mov_b32_e32 v31, v56
	v_mov_b32_e32 v56, v53
	v_pk_mul_f32 v[30:31], v[42:43], v[30:31] op_sel_hi:[0,1]
	v_pk_mul_f32 v[52:53], v[42:43], v[56:57] op_sel_hi:[0,1]
	s_waitcnt lgkmcnt(0)
	v_pk_fma_f32 v[10:11], v[50:51], v[52:53], v[10:11]
	v_pk_fma_f32 v[8:9], v[48:49], v[30:31], v[8:9]
	v_cvt_pk_bf16_f32 v31, v10, v11
	v_cvt_pk_bf16_f32 v30, v8, v9
	global_store_dwordx2 v[36:37], v[30:31], off offset:2560 nt
	v_pk_mul_f32 v[30:31], v[10:11], v[10:11]
	v_pk_mul_f32 v[48:49], v[8:9], v[8:9]
	v_pk_mul_f32 v[46:47], v[42:43], v[46:47] op_sel_hi:[0,1]
	v_pk_mov_b32 v[50:51], v[48:49], v[30:31] op_sel:[1,0]
	v_mov_b32_e32 v49, v31
	v_pk_add_f32 v[30:31], v[50:51], v[48:49]
	ds_read_b128 v[48:51], v54 offset:6144
	v_pk_add_f32 v[24:25], v[24:25], v[24:25] op_sel_hi:[0,1]
	v_mov_b32_e32 v40, v43
	v_pk_mul_f32 v[40:41], v[40:41], v[42:43] op_sel_hi:[1,0]
	v_pk_mul_f32 v[38:39], v[38:39], v[42:43] op_sel_hi:[1,0]
	s_waitcnt lgkmcnt(0)
	v_pk_fma_f32 v[6:7], v[50:51], v[46:47], v[6:7]
	v_pk_fma_f32 v[4:5], v[48:49], v[44:45], v[4:5]
	v_cvt_pk_bf16_f32 v45, v6, v7
	v_cvt_pk_bf16_f32 v44, v4, v5
	global_store_dwordx2 v[36:37], v[44:45], off offset:3072 nt
	ds_read_b128 v[44:47], v54 offset:7168
	v_mul_f32_e32 v24, v4, v4
	v_pk_fma_f32 v[48:49], v[4:5], v[4:5], v[24:25] op_sel_hi:[1,1,0]
	v_mul_f32_e32 v24, v6, v6
	v_pk_add_f32 v[30:31], v[30:31], v[30:31] op_sel_hi:[0,1]
	v_pk_fma_f32 v[50:51], v[6:7], v[6:7], v[24:25] op_sel_hi:[1,1,0]
	s_waitcnt lgkmcnt(0)
	v_pk_fma_f32 v[2:3], v[46:47], v[38:39], v[2:3]
	v_pk_fma_f32 v[0:1], v[44:45], v[40:41], v[0:1]
	v_cvt_pk_bf16_f32 v39, v2, v3
	v_cvt_pk_bf16_f32 v38, v0, v1
	v_mul_f32_e32 v48, v0, v0
	v_mul_f32_e32 v50, v1, v1
	v_mul_f32_e32 v30, v2, v2
	v_mul_f32_e32 v24, v3, v3
	global_store_dwordx2 v[36:37], v[38:39], off offset:3584 nt
	v_pk_add_f32 v[38:39], v[48:49], v[50:51]
	v_pk_add_f32 v[24:25], v[30:31], v[24:25]
	v_add_u32_e32 v32, s42, v32
	v_pk_add_f32 v[24:25], v[38:39], v[24:25]
	ds_read_b128 v[38:41], v54 offset:16384
	ds_read_b128 v[42:45], v54 offset:32768
	v_add_f32_e32 v24, v24, v25
	s_nop 1
	v_add_f32_dpp v24, v24, v24 quad_perm:[1,0,3,2] row_mask:0xf bank_mask:0xf
	s_nop 1
	v_add_f32_dpp v24, v24, v24 quad_perm:[2,3,0,1] row_mask:0xf bank_mask:0xf
	s_nop 1
	v_add_f32_dpp v24, v24, v24 row_half_mirror row_mask:0xf bank_mask:0xf
	s_nop 1
	v_add_f32_dpp v24, v24, v24 row_mirror row_mask:0xf bank_mask:0xf
	v_mov_b32_e32 v25, v24
	s_nop 1
	v_permlane16_swap_b32_e32 v25, v24
	v_add_f32_e32 v24, v24, v25
	v_mov_b32_e32 v25, v24
	s_nop 1
	v_permlane32_swap_b32_e32 v25, v24
	v_add_f32_e32 v24, v24, v25
	s_waitcnt lgkmcnt(0)
; #define LAS __attribute__((address_space(3)))
; __device__ __forceinline__ unsigned pk2(float lo, float hi) { return pg8::cvtpk(lo, hi); }
; __device__ __forceinline__ void p7_rows(const Params& P, LAS unsigned char* lds, int G) {
;     ...
;         const float rstd2 = rsqrtf(wave_sum(s2) * (1.0f / DM) + RMS_EPS);
;         u32x2* o = (u32x2*)(XN + (size_t)m * DM) + lane;
; #pragma unroll
;         for (int j = 0; j < 8; ++j) { const f32x4 a = *(const LAS f32x4*)(TB + b * DM + 256 * j + 4 * lane), c = *(const LAS f32x4*)(TC + b * DM + 256 * j + 4 * lane);
;             const f32x4 h = v[j] * rstd2 * a + c; u32x2 w; w.x = pk2(h[0], h[1]); w.y = pk2(h[2], h[3]); o[64 * j] = w; }
	v_fmamk_f32 v24, v24, 0x3a000000, v33
	v_cmp_gt_f32_e32 vcc, s3, v24
	v_mul_f32_e32 v25, 0x4b800000, v24
	s_nop 0
	v_cndmask_b32_e32 v24, v24, v25, vcc
	v_rsq_f32_e32 v24, v24
	s_nop 0
	v_mul_f32_e32 v25, 0x45800000, v24
	v_cndmask_b32_e32 v24, v24, v25, vcc
	v_pk_mul_f32 v[30:31], v[82:83], v[24:25] op_sel_hi:[1,0]
	v_pk_mul_f32 v[46:47], v[84:85], v[24:25] op_sel_hi:[1,0]
	v_pk_fma_f32 v[30:31], v[38:39], v[30:31], v[42:43]
	v_pk_fma_f32 v[40:41], v[40:41], v[46:47], v[44:45]
	v_add_co_u32_e32 v38, vcc, s33, v36
	v_cvt_pk_bf16_f32 v30, v30, v31
	v_cvt_pk_bf16_f32 v31, v40, v41
	v_addc_co_u32_e32 v39, vcc, -1, v37, vcc
	global_store_dwordx2 v[38:39], v[30:31], off
	ds_read_b128 v[38:41], v54 offset:17408
	ds_read_b128 v[42:45], v54 offset:33792
	v_pk_mul_f32 v[28:29], v[28:29], v[24:25] op_sel_hi:[1,0]
	v_pk_mul_f32 v[26:27], v[26:27], v[24:25] op_sel_hi:[1,0]
	s_mov_b32 s33, 0xec801000
	v_pk_mul_f32 v[20:21], v[20:21], v[24:25] op_sel_hi:[1,0]
	s_waitcnt lgkmcnt(0)
	v_pk_fma_f32 v[30:31], v[40:41], v[26:27], v[44:45]
	v_pk_fma_f32 v[26:27], v[38:39], v[28:29], v[42:43]
	v_pk_mul_f32 v[22:23], v[22:23], v[24:25] op_sel_hi:[1,0]
	v_cvt_pk_bf16_f32 v26, v26, v27
	v_cvt_pk_bf16_f32 v27, v30, v31
	v_add_co_u32_e32 v30, vcc, s33, v36
	v_pk_mul_f32 v[16:17], v[16:17], v[24:25] op_sel_hi:[1,0]
	s_nop 0
	v_addc_co_u32_e32 v31, vcc, -1, v37, vcc
	global_store_dwordx2 v[30:31], v[26:27], off offset:-3584
	ds_read_b128 v[26:29], v54 offset:18432
	ds_read_b128 v[38:41], v54 offset:34816
	v_pk_mul_f32 v[18:19], v[18:19], v[24:25] op_sel_hi:[1,0]
	v_pk_mul_f32 v[12:13], v[12:13], v[24:25] op_sel_hi:[1,0]
	v_pk_mul_f32 v[14:15], v[14:15], v[24:25] op_sel_hi:[1,0]
	v_pk_mul_f32 v[8:9], v[8:9], v[24:25] op_sel_hi:[1,0]
	s_waitcnt lgkmcnt(0)
	v_pk_fma_f32 v[22:23], v[28:29], v[22:23], v[40:41]
	v_pk_fma_f32 v[20:21], v[26:27], v[20:21], v[38:39]
	v_pk_mul_f32 v[10:11], v[10:11], v[24:25] op_sel_hi:[1,0]
	v_cvt_pk_bf16_f32 v20, v20, v21
	v_cvt_pk_bf16_f32 v21, v22, v23
	global_store_dwordx2 v[30:31], v[20:21], off offset:-3072
	ds_read_b128 v[20:23], v54 offset:19456
	ds_read_b128 v[26:29], v54 offset:35840
	v_pk_mul_f32 v[4:5], v[4:5], v[24:25] op_sel_hi:[1,0]
	v_pk_mul_f32 v[6:7], v[6:7], v[24:25] op_sel_hi:[1,0]
	v_pk_mul_f32 v[0:1], v[0:1], v[24:25] op_sel_hi:[1,0]
	v_pk_mul_f32 v[2:3], v[2:3], v[24:25] op_sel_hi:[1,0]
	s_waitcnt lgkmcnt(0)
	v_pk_fma_f32 v[18:19], v[22:23], v[18:19], v[28:29]
	v_pk_fma_f32 v[16:17], v[20:21], v[16:17], v[26:27]
	s_and_b32 s33, s2, 7
	s_lshl_b32 s33, s33, 11
	s_addk_i32 s33, 0x7ff
	s_cmpk_eq_u32 s92, 0x100
	s_cselect_b32 s33, s33, 0x3fff
	v_cvt_pk_bf16_f32 v16, v16, v17
	v_cvt_pk_bf16_f32 v17, v18, v19
	global_store_dwordx2 v[30:31], v[16:17], off offset:-2560
	ds_read_b128 v[16:19], v54 offset:20480
	ds_read_b128 v[20:23], v54 offset:36864
	v_cmp_lt_i32_e32 vcc, s33, v32
	v_lshl_add_u64 v[36:37], v[36:37], 0, s[26:27]
	s_or_b64 s[30:31], vcc, s[30:31]
	s_waitcnt lgkmcnt(0)
	v_pk_fma_f32 v[14:15], v[18:19], v[14:15], v[22:23]
	v_pk_fma_f32 v[12:13], v[16:17], v[12:13], v[20:21]
	s_nop 0
	v_cvt_pk_bf16_f32 v12, v12, v13
	v_cvt_pk_bf16_f32 v13, v14, v15
	global_store_dwordx2 v[30:31], v[12:13], off offset:-2048
	ds_read_b128 v[12:15], v54 offset:21504
	ds_read_b128 v[16:19], v54 offset:37888
	s_waitcnt lgkmcnt(0)
	v_pk_fma_f32 v[10:11], v[14:15], v[10:11], v[18:19]
	v_pk_fma_f32 v[8:9], v[12:13], v[8:9], v[16:17]
	s_nop 0
	v_cvt_pk_bf16_f32 v8, v8, v9
	v_cvt_pk_bf16_f32 v9, v10, v11
	global_store_dwordx2 v[30:31], v[8:9], off offset:-1536
	ds_read_b128 v[8:11], v54 offset:22528
	ds_read_b128 v[12:15], v54 offset:38912
	s_waitcnt lgkmcnt(0)
	v_pk_fma_f32 v[6:7], v[10:11], v[6:7], v[14:15]
	v_pk_fma_f32 v[4:5], v[8:9], v[4:5], v[12:13]
	s_nop 0
	v_cvt_pk_bf16_f32 v4, v4, v5
	v_cvt_pk_bf16_f32 v5, v6, v7
	global_store_dwordx2 v[30:31], v[4:5], off offset:-1024
	ds_read_b128 v[4:7], v54 offset:23552
	ds_read_b128 v[8:11], v54 offset:39936
	s_waitcnt lgkmcnt(0)
	v_pk_fma_f32 v[2:3], v[6:7], v[2:3], v[10:11]
	v_pk_fma_f32 v[0:1], v[4:5], v[0:1], v[8:9]
	s_nop 0
	v_cvt_pk_bf16_f32 v0, v0, v1
	v_cvt_pk_bf16_f32 v1, v2, v3
	global_store_dwordx2 v[30:31], v[0:1], off offset:-512
	s_andn2_b64 exec, exec, s[30:31]
	s_cbranch_execnz .LBB0_803
